# attention tile-prefetch addressing folded into per-item pointers (12+8 fewer VALU per loop iteration), redundant canonicalising max ops removed
# baseline (speedup 1.0000x reference)
; #define GLOAD(kt_, KR, VR) do { _Pragma("unroll") for (int i = 0; i < KCH; ++i) if (krow_[i] < 64) KR[i] = *(const u32x4*)(kbase + (size_t)((kt_) * 64 + krow_[i]) * HK * DQ + kcol_[i]); \
;     VR = *(const u32x4*)(vbase + (size_t)(kt_) * 4096 + vrow * 64 + vcol); } while (0)
; #define LSTORE(buf_, KR, VR) do { _Pragma("unroll") for (int i = 0; i < KCH; ++i) if (krow_[i] < 64) *(u32x4*)(sK + (buf_) * 64 * KROW + krow_[i] * KROW + kcol_[i]) = KR[i]; \
;     u16* d_ = sV + (buf_) * 64 * VROW + vrow * VROW + (vcol >> 4) * 16 + ((vcol >> 3) & 1) * 4; u32x2 lo_ = {VR.x, VR.y}, hi_ = {VR.z, VR.w}; *(u32x2*)d_ = lo_; *(u32x2*)(d_ + 8) = hi_; } while (0)
; template <int DQ>
; DI void attn_dense_item(const u16* __restrict__ Q, int qh, const u16* __restrict__ Kp, int HK, int kh, const u16* __restrict__ Vt,
;                         int S, int s0, int qblk, u16* __restrict__ MER, int ocol, float* __restrict__ ssqo, int slot, unsigned char* smem) {
;     ...
;   const u16* kbase = Kp + ((size_t)s0 * HK + kh) * DQ;
;   const u16* vbase = Vt + (size_t)s0 * HK * 64 + (size_t)(kh * 64) * S;
;   int krow_[KCH], kcol_[KCH];
; #pragma unroll
;   for (int i = 0; i < KCH; ++i) { const int c = tid + 512 * i; krow_[i] = c / CPR; kcol_[i] = (c - krow_[i] * CPR) * 8; }
;   const int vrow = tid >> 3, vcol = (tid & 7) * 8;
;   u32x4 krA[KCH], vrA, krB[KCH], vrB;
;     ...
;   const int nkt = S >> 6;
;   GLOAD(0, krA, vrA); GLOAD(1, krB, vrB); LSTORE(0, krA, vrA); LSTORE(1, krB, vrB);
;   GLOAD(2, krA, vrA); GLOAD(3, krB, vrB);
;   __syncthreads();
;   f32x16 o[2];
;   float lrun = 0.f;
;   f32x16 negm;
; #pragma unroll
;   for (int i = 0; i < 16; ++i) { o[0][i] = 0.f; o[1][i] = 0.f; negm[i] = 0.f; }
.LBB0_297:
	s_or_b64 exec, exec, s[6:7]
	v_add_f32_e32 v50, 0, v158
	v_add_f32_e32 v50, v159, v50
	v_add_f32_e32 v50, v160, v50
	v_add_f32_e32 v50, v161, v50
	v_add_f32_e32 v50, v215, v50
	s_mov_b32 s6, 0xa000
	v_add_f32_e32 v52, v216, v50
	v_add_co_u32_e32 v50, vcc, s6, v80
	v_add_f32_e32 v0, v0, v52
	s_nop 0
	v_addc_co_u32_e32 v51, vcc, 0, v81, vcc
	global_load_dwordx4 v[158:161], v[50:51], off
	v_add_f32_e32 v0, v62, v0
	v_add_f32_e32 v0, v63, v0
	v_add_f32_e32 v0, v64, v0
	v_add_f32_e32 v0, v65, v0
	v_add_f32_e32 v0, v88, v0
	v_add_f32_e32 v0, v89, v0
	v_add_f32_e32 v0, v90, v0
	v_add_f32_e32 v0, v91, v0
	v_add_f32_e32 v0, v92, v0
	v_add_f32_e32 v0, v93, v0
	v_add_f32_e32 v0, v94, v0
	v_add_f32_e32 v0, v95, v0
	v_add_f32_e32 v0, v96, v0
	v_add_f32_e32 v0, v97, v0
	v_add_f32_e32 v0, v98, v0
	v_add_f32_e32 v0, v99, v0
	v_add_f32_e32 v0, v100, v0
	v_add_f32_e32 v0, v101, v0
	v_add_f32_e32 v0, v102, v0
	v_add_f32_e32 v0, v103, v0
	v_add_f32_e32 v0, v104, v0
	v_add_f32_e32 v0, v105, v0
	v_add_f32_e32 v0, v106, v0
	v_add_f32_e32 v0, v107, v0
	v_add_f32_e32 v0, v108, v0
	v_add_f32_e32 v0, v110, v0
	v_add_f32_e32 v0, v111, v0
	v_add_f32_e32 v0, v112, v0
	v_add_f32_e32 v0, v113, v0
	v_add_f32_e32 v0, v162, v0
	v_add_f32_e32 v0, v163, v0
	v_add_f32_e32 v0, v164, v0
	v_add_f32_e32 v0, v165, v0
	v_add_f32_e32 v0, v166, v0
	v_add_f32_e32 v0, v167, v0
	v_add_f32_e32 v0, v168, v0
	v_add_f32_e32 v0, v169, v0
	v_add_f32_e32 v0, v174, v0
	v_add_f32_e32 v0, v175, v0
	v_add_f32_e32 v0, v176, v0
	v_add_f32_e32 v0, v177, v0
	v_add_f32_e32 v0, v178, v0
	v_add_f32_e32 v0, v179, v0
	v_add_f32_e32 v0, v201, v0
	v_add_f32_e32 v0, v202, v0
	v_add_f32_e32 v0, v203, v0
	v_add_f32_e32 v0, v204, v0
	v_add_f32_e32 v0, v205, v0
	v_add_f32_e32 v0, v206, v0
	v_add_f32_e32 v0, v207, v0
	v_add_f32_e32 v0, v208, v0
	v_add_f32_e32 v0, v209, v0
	v_add_f32_e32 v0, v210, v0
	v_add_f32_e32 v0, v211, v0
	v_add_f32_e32 v0, v212, v0
	v_add_f32_e32 v0, v213, v0
	v_add_f32_e32 v201, v214, v0
	v_and_b32_e32 v0, 7, v82
	s_add_u32 s6, s14, s28
	v_lshlrev_b32_e32 v0, 4, v0
	s_addc_u32 s7, s15, s27
	v_lshl_add_u64 v[50:51], s[6:7], 0, v[0:1]
	s_mul_hi_i32 s7, s25, 0x480
	s_mul_i32 s6, s25, 0x480
	v_lshl_add_u64 v[174:175], v[78:79], 1, v[50:51]
	v_mov_b64_e32 v[50:51], s[6:7]
	s_waitcnt lgkmcnt(0)
	s_barrier
	v_mad_i64_i32 v[52:53], s[6:7], v83, s33, v[50:51]
	v_mad_i64_i32 v[50:51], s[6:7], v84, s33, v[50:51]
	v_sub_f32_e32 v34, 0, v109
	v_mad_i64_i32 v[52:53], s[6:7], s10, v184, v[52:53]
	v_mad_i64_i32 v[50:51], s[6:7], s10, v184, v[50:51]
	v_ashrrev_i32_e32 v171, 31, v170
	v_mul_u32_u24_e32 v199, 0xd0, v85
	v_mul_u32_u24_e32 v200, 0x90, v85
	v_mov_b32_e32 v35, v34
	v_mov_b32_e32 v36, v34
	v_mov_b32_e32 v37, v34
	v_mov_b32_e32 v38, v34
	v_mov_b32_e32 v39, v34
	v_mov_b32_e32 v40, v34
	v_mov_b32_e32 v41, v34
	v_mov_b32_e32 v42, v34
	v_mov_b32_e32 v43, v34
	v_mov_b32_e32 v44, v34
	v_mov_b32_e32 v45, v34
	v_mov_b32_e32 v46, v34
	v_mov_b32_e32 v47, v34
	v_mov_b32_e32 v48, v34
	v_mov_b32_e32 v49, v34
	v_lshl_add_u64 v[176:177], v[74:75], 1, v[52:53]
	v_lshl_add_u64 v[178:179], v[76:77], 1, v[50:51]
	s_mov_b64 vcc, 0x2ef4c000
	v_lshl_add_u64 v[176:177], s[90:91], 0, v[176:177]
	v_lshl_add_u64 v[178:179], s[90:91], 0, v[178:179]
	v_lshl_add_u64 v[176:177], v[176:177], 0, vcc
	v_lshl_add_u64 v[178:179], v[178:179], 0, vcc
	s_mov_b64 vcc, 0x35aec000
	v_lshl_add_u64 v[174:175], s[90:91], 0, v[174:175]
	v_lshl_add_u64 v[174:175], v[174:175], 0, vcc
	v_mov_b32_e32 v74, 0
	v_mov_b32_e32 v75, 0
	v_mov_b32_e32 v76, 0
	v_mov_b32_e32 v77, 0
	v_mov_b32_e32 v78, 0
	v_mov_b32_e32 v79, 0
	v_mov_b32_e32 v80, 0
	v_mov_b32_e32 v81, 0
	v_mov_b32_e32 v82, 0
	v_mov_b32_e32 v83, 0
	v_mov_b32_e32 v84, 0
	v_mov_b32_e32 v85, 0
	v_mov_b32_e32 v86, 0
	v_mov_b32_e32 v87, 0
	v_mov_b32_e32 v88, 0
	v_mov_b32_e32 v89, 0
	v_mov_b32_e32 v90, 0
	v_mov_b32_e32 v91, 0
	v_mov_b32_e32 v92, 0
	v_mov_b32_e32 v93, 0
	v_mov_b32_e32 v94, 0
	v_mov_b32_e32 v95, 0
	v_mov_b32_e32 v96, 0
	v_mov_b32_e32 v97, 0
	v_mov_b32_e32 v98, 0
	v_mov_b32_e32 v99, 0
	v_mov_b32_e32 v100, 0
	v_mov_b32_e32 v101, 0
	v_mov_b32_e32 v102, 0
	v_mov_b32_e32 v103, 0
	v_mov_b32_e32 v104, 0
	v_mov_b32_e32 v105, 0
	v_mov_b32_e32 v106, 0
	v_mov_b32_e32 v107, 0
	v_mov_b32_e32 v108, 0
	v_mov_b32_e32 v109, 0
	v_mov_b32_e32 v110, 0
	v_mov_b32_e32 v111, 0
	v_mov_b32_e32 v112, 0
	v_mov_b32_e32 v113, 0
	v_mov_b32_e32 v246, 0
	v_mov_b32_e32 v202, 0
	v_mov_b32_e32 v203, 0
	v_mov_b32_e32 v204, 0
	v_mov_b32_e32 v205, 0
	v_mov_b32_e32 v206, 0
	v_mov_b32_e32 v207, 0
	v_mov_b32_e32 v208, 0
	v_mov_b32_e32 v209, 0
	v_mov_b32_e32 v210, 0
	v_mov_b32_e32 v211, 0
	v_mov_b32_e32 v212, 0
	v_mov_b32_e32 v213, 0
	v_mov_b32_e32 v214, 0
	v_mov_b32_e32 v215, 0
	v_mov_b32_e32 v216, 0
	v_mov_b32_e32 v217, 0
	v_mov_b32_e32 v218, 0
	v_mov_b32_e32 v219, 0
	v_mov_b32_e32 v220, 0
	v_mov_b32_e32 v221, 0
	v_mov_b32_e32 v222, 0
	v_mov_b32_e32 v223, 0
	v_mov_b32_e32 v224, 0
	s_mov_b32 s14, 6
	s_branch .LBB0_300

.Lmla_B_312:
	s_cmp_ge_u32 s14, s23
	s_cbranch_scc1 .Lmla_B_ls_end
	s_mov_b64 vcc, 0x12000
	v_lshl_add_u64 v[50:51], v[176:177], 0, vcc
	v_lshl_add_u64 v[52:53], v[178:179], 0, vcc
	s_mov_b64 vcc, 0x2000
	v_lshl_add_u64 v[54:55], v[174:175], 0, vcc
	s_and_saveexec_b64 s[6:7], s[0:1]
	s_cbranch_execz .Lmla_B_315
	global_load_dwordx4 v[138:141], v[176:177], off
.Lmla_B_315:
	s_or_b64 exec, exec, s[6:7]
	s_and_saveexec_b64 s[6:7], s[4:5]
	s_cbranch_execz .Lmla_B_317
	global_load_dwordx4 v[142:145], v[178:179], off
.Lmla_B_317:
	s_or_b64 exec, exec, s[6:7]
	global_load_dwordx4 v[154:157], v[174:175], off
	s_and_saveexec_b64 s[6:7], s[0:1]
	s_cbranch_execz .Lmla_B_319
	global_load_dwordx4 v[146:149], v[50:51], off
.Lmla_B_319:
	s_or_b64 exec, exec, s[6:7]
	s_and_saveexec_b64 s[6:7], s[4:5]
	s_cbranch_execz .Lmla_B_298
	global_load_dwordx4 v[150:153], v[52:53], off
.Lmla_B_298:
	s_or_b64 exec, exec, s[6:7]
	global_load_dwordx4 v[158:161], v[54:55], off
.Lmla_B_ls_end:
	s_add_i32 s6, s14, -4
	s_and_b32 s6, s6, 2
	s_mul_i32 s7, s6, 0x2400
	v_add_f32_e32 v201, v74, v201
	v_add_f32_e32 v247, v75, v76
	v_add_f32_e32 v201, v77, v201
	v_add_f32_e32 v247, v78, v247
	v_add_f32_e32 v201, v79, v201
	v_add_f32_e32 v247, v80, v247
	v_add_f32_e32 v201, v81, v201
	v_add_f32_e32 v247, v82, v247
	v_add_f32_e32 v201, v83, v201
	v_add_f32_e32 v247, v84, v247
	v_add_f32_e32 v201, v85, v201
	v_add_f32_e32 v247, v86, v247
	v_add_f32_e32 v201, v87, v201
	v_add_f32_e32 v247, v88, v247
	s_waitcnt lgkmcnt(6)
	v_mfma_f32_32x32x16_bf16 v[50:65], v[226:229], v[114:117], v[34:49]
	ds_read_b128 v[226:229], v0 offset:6688
	v_add_f32_e32 v201, v89, v201
	v_add_f32_e32 v247, v90, v247
	v_add_f32_e32 v201, v91, v201
	v_add_f32_e32 v247, v92, v247
	v_add_f32_e32 v201, v93, v201
	s_waitcnt lgkmcnt(6)
	v_mfma_f32_32x32x16_bf16 v[50:65], v[230:233], v[118:121], v[50:65]
	ds_read_b128 v[230:233], v0 offset:6720
	v_add_f32_e32 v247, v94, v247
	v_add_f32_e32 v201, v95, v201
	v_add_f32_e32 v247, v96, v247
	v_add_f32_e32 v201, v97, v201
	v_add_f32_e32 v247, v98, v247
	s_waitcnt lgkmcnt(6)
	v_mfma_f32_32x32x16_bf16 v[50:65], v[234:237], v[122:125], v[50:65]
	ds_read_b128 v[234:237], v0 offset:6752
	v_add_f32_e32 v201, v99, v201
	v_add_f32_e32 v247, v100, v247
	v_add_f32_e32 v201, v101, v201
	v_add_f32_e32 v247, v102, v247
	s_waitcnt lgkmcnt(6)
	v_mfma_f32_32x32x16_bf16 v[50:65], v[238:241], v[126:129], v[50:65]
	ds_read_b128 v[238:241], v0 offset:6784
	v_add_f32_e32 v201, v103, v201
	v_add_f32_e32 v247, v104, v247
	v_add_f32_e32 v201, v105, v201
	v_add_f32_e32 v247, v106, v247
	s_waitcnt lgkmcnt(6)
	v_mfma_f32_32x32x16_bf16 v[50:65], v[242:245], v[130:133], v[50:65]
	ds_read_b128 v[242:245], v0 offset:6816
	v_add_f32_e32 v201, v107, v201
	v_add_f32_e32 v247, v108, v247
	v_add_f32_e32 v201, v109, v201
	v_add_f32_e32 v247, v110, v247
	s_waitcnt lgkmcnt(6)
	v_mfma_f32_32x32x16_bf16 v[50:65], v[162:165], v[134:137], v[50:65]
	ds_read_b128 v[162:165], v225
	v_add_f32_e32 v201, v111, v201
	v_add_f32_e32 v247, v112, v247
	v_add_f32_e32 v201, v113, v201
	v_add_f32_e32 v247, v246, v247
	s_waitcnt lgkmcnt(6)
	v_mfma_f32_32x32x16_bf16 v[66:81], v[166:169], v[114:117], v[34:49]
	ds_read_b128 v[166:169], v225 offset:32
	v_add_f32_e32 v201, v202, v201
	v_add_f32_e32 v247, v203, v247
	v_add_f32_e32 v201, v204, v201
	v_add_f32_e32 v247, v205, v247
	s_waitcnt lgkmcnt(6)
	v_mfma_f32_32x32x16_bf16 v[66:81], v[226:229], v[118:121], v[66:81]
	ds_read_b128 v[226:229], v225 offset:64
	v_add_f32_e32 v201, v206, v201
	v_add_f32_e32 v247, v207, v247
	v_add_f32_e32 v201, v208, v201
	v_add_f32_e32 v247, v209, v247
	s_waitcnt lgkmcnt(6)
	v_mfma_f32_32x32x16_bf16 v[66:81], v[230:233], v[122:125], v[66:81]
	ds_read_b128 v[230:233], v225 offset:96
	v_add_f32_e32 v201, v210, v201
	v_add_f32_e32 v247, v211, v247
	v_add_f32_e32 v201, v212, v201
	v_add_f32_e32 v247, v213, v247
	v_max3_f32 v0, v50, v51, v52
	v_max3_f32 v0, v0, v53, v54
	s_waitcnt lgkmcnt(6)
	v_mfma_f32_32x32x16_bf16 v[66:81], v[234:237], v[126:129], v[66:81]
	ds_read_b128 v[234:237], v225 offset:128
	v_add_f32_e32 v201, v214, v201
	v_add_f32_e32 v247, v215, v247
	v_add_f32_e32 v201, v216, v201
	v_add_f32_e32 v247, v217, v247
	v_max3_f32 v0, v0, v55, v56
	v_max3_f32 v0, v0, v57, v58
	s_waitcnt lgkmcnt(6)
	v_mfma_f32_32x32x16_bf16 v[66:81], v[238:241], v[130:133], v[66:81]
	ds_read_b128 v[238:241], v225 offset:160
	v_add_f32_e32 v201, v218, v201
	v_add_f32_e32 v247, v219, v247
	v_add_f32_e32 v201, v220, v201
	v_add_f32_e32 v247, v221, v247
	v_max3_f32 v0, v0, v59, v60
	v_max3_f32 v0, v0, v61, v62
	s_waitcnt lgkmcnt(6)
	v_mfma_f32_32x32x16_bf16 v[66:81], v[242:245], v[134:137], v[66:81]
	ds_read_b128 v[242:245], v225 offset:6656
	v_add_f32_e32 v201, v222, v201
	v_add_f32_e32 v247, v223, v247
	v_add_f32_e32 v201, v224, v201
	v_add_f32_e32 v201, v247, v201
	v_max3_f32 v0, v0, v63, v64
	v_max3_f32 v0, v0, v65, v65
	s_waitcnt lgkmcnt(6)
	v_mfma_f32_32x32x16_bf16 v[82:97], v[162:165], v[114:117], v[34:49]
	ds_read_b128 v[162:165], v225 offset:6688
	s_waitcnt lgkmcnt(6)
	v_mfma_f32_32x32x16_bf16 v[82:97], v[166:169], v[118:121], v[82:97]
	ds_read_b128 v[166:169], v225 offset:6720
	v_add3_u32 v247, v198, s7, v200
	s_waitcnt lgkmcnt(6)
	v_mfma_f32_32x32x16_bf16 v[82:97], v[226:229], v[122:125], v[82:97]
	ds_read_b128 v[226:229], v225 offset:6752
	v_max3_f32 v0, v0, v66, v67
	v_max3_f32 v0, v0, v68, v69
	s_waitcnt lgkmcnt(6)
	v_mfma_f32_32x32x16_bf16 v[82:97], v[230:233], v[126:129], v[82:97]
	ds_read_b128 v[230:233], v225 offset:6784
	v_max3_f32 v0, v0, v70, v71
	v_max3_f32 v0, v0, v72, v73
	s_waitcnt lgkmcnt(6)
	v_mfma_f32_32x32x16_bf16 v[82:97], v[234:237], v[130:133], v[82:97]
	ds_read_b128 v[234:237], v225 offset:6816
	v_max3_f32 v0, v0, v74, v75
	v_max3_f32 v0, v0, v76, v77
	s_waitcnt lgkmcnt(6)
	v_mfma_f32_32x32x16_bf16 v[82:97], v[238:241], v[134:137], v[82:97]
	ds_read_b128 v[238:241], v247 offset:53248
	v_max3_f32 v0, v0, v78, v79
	v_max3_f32 v0, v0, v80, v81
	s_waitcnt lgkmcnt(6)
	v_mfma_f32_32x32x16_bf16 v[98:113], v[242:245], v[114:117], v[34:49]
	ds_read_b128 v[242:245], v247 offset:57856
	s_waitcnt lgkmcnt(6)
	v_mfma_f32_32x32x16_bf16 v[98:113], v[162:165], v[118:121], v[98:113]
	s_waitcnt lgkmcnt(5)
	v_mfma_f32_32x32x16_bf16 v[98:113], v[166:169], v[122:125], v[98:113]
	s_waitcnt lgkmcnt(4)
	v_mfma_f32_32x32x16_bf16 v[98:113], v[226:229], v[126:129], v[98:113]
	ds_read_b128 v[226:229], v247 offset:53280
	s_waitcnt lgkmcnt(4)
	v_mfma_f32_32x32x16_bf16 v[98:113], v[230:233], v[130:133], v[98:113]
	ds_read_b128 v[230:233], v247 offset:57888
	s_waitcnt lgkmcnt(4)
	v_mfma_f32_32x32x16_bf16 v[98:113], v[234:237], v[134:137], v[98:113]
	ds_read_b128 v[234:237], v247 offset:53312
	v_max3_f32 v0, v0, v82, v83
	v_max3_f32 v0, v0, v84, v85
	v_max3_f32 v0, v0, v86, v87
	v_max3_f32 v0, v0, v88, v89
	v_max3_f32 v0, v0, v90, v91
	v_max3_f32 v0, v0, v92, v93
	v_max3_f32 v0, v0, v94, v95
	v_max3_f32 v0, v0, v96, v97
	s_nop 4
	v_max3_f32 v0, v0, v98, v99
	v_max3_f32 v0, v0, v100, v101
	v_max3_f32 v0, v0, v102, v103
	v_max3_f32 v0, v0, v104, v105
	v_max3_f32 v0, v0, v106, v107
	v_max3_f32 v0, v0, v108, v109
	v_max3_f32 v0, v0, v110, v111
	v_max3_f32 v0, v0, v112, v113
	v_mov_b32_e32 v162, v0
	s_nop 1
	v_permlane32_swap_b32_e32 v0, v162
	v_max_f32_e32 v0, v0, v162
	v_cmp_lt_f32_e32 vcc, s50, v0
	s_cbranch_vccz .LBB0_302
	v_max_f32_e32 v0, v0, v0
	v_max_f32_e32 v0, 0, v0
	v_exp_f32_e64 v162, -v0
	v_pk_add_f32 v[50:51], v[50:51], v[0:1] op_sel_hi:[1,0] neg_lo:[0,1] neg_hi:[0,1]
	v_pk_add_f32 v[66:67], v[66:67], v[0:1] op_sel_hi:[1,0] neg_lo:[0,1] neg_hi:[0,1]
	v_pk_add_f32 v[82:83], v[82:83], v[0:1] op_sel_hi:[1,0] neg_lo:[0,1] neg_hi:[0,1]
	v_mul_f32_e32 v201, v201, v162
	v_pk_mul_f32 v[16:17], v[16:17], v[162:163] op_sel_hi:[1,0]
	v_pk_mul_f32 v[14:15], v[14:15], v[162:163] op_sel_hi:[1,0]
	v_pk_mul_f32 v[12:13], v[12:13], v[162:163] op_sel_hi:[1,0]
	v_pk_mul_f32 v[10:11], v[10:11], v[162:163] op_sel_hi:[1,0]
	v_pk_mul_f32 v[8:9], v[8:9], v[162:163] op_sel_hi:[1,0]
	v_pk_mul_f32 v[6:7], v[6:7], v[162:163] op_sel_hi:[1,0]
	v_pk_mul_f32 v[4:5], v[4:5], v[162:163] op_sel_hi:[1,0]
	v_pk_mul_f32 v[2:3], v[2:3], v[162:163] op_sel_hi:[1,0]
	v_pk_mul_f32 v[32:33], v[32:33], v[162:163] op_sel_hi:[1,0]
	v_pk_mul_f32 v[30:31], v[30:31], v[162:163] op_sel_hi:[1,0]
	v_pk_mul_f32 v[28:29], v[28:29], v[162:163] op_sel_hi:[1,0]
	v_pk_mul_f32 v[26:27], v[26:27], v[162:163] op_sel_hi:[1,0]
	v_pk_mul_f32 v[24:25], v[24:25], v[162:163] op_sel_hi:[1,0]
	v_pk_mul_f32 v[22:23], v[22:23], v[162:163] op_sel_hi:[1,0]
	v_pk_mul_f32 v[20:21], v[20:21], v[162:163] op_sel_hi:[1,0]
	v_pk_mul_f32 v[18:19], v[18:19], v[162:163] op_sel_hi:[1,0]
	v_pk_add_f32 v[98:99], v[98:99], v[0:1] op_sel_hi:[1,0] neg_lo:[0,1] neg_hi:[0,1]
	v_pk_add_f32 v[52:53], v[52:53], v[0:1] op_sel_hi:[1,0] neg_lo:[0,1] neg_hi:[0,1]
	v_pk_add_f32 v[68:69], v[68:69], v[0:1] op_sel_hi:[1,0] neg_lo:[0,1] neg_hi:[0,1]
	v_pk_add_f32 v[84:85], v[84:85], v[0:1] op_sel_hi:[1,0] neg_lo:[0,1] neg_hi:[0,1]
	v_pk_add_f32 v[100:101], v[100:101], v[0:1] op_sel_hi:[1,0] neg_lo:[0,1] neg_hi:[0,1]
	v_pk_add_f32 v[54:55], v[54:55], v[0:1] op_sel_hi:[1,0] neg_lo:[0,1] neg_hi:[0,1]
	v_pk_add_f32 v[70:71], v[70:71], v[0:1] op_sel_hi:[1,0] neg_lo:[0,1] neg_hi:[0,1]
	v_pk_add_f32 v[86:87], v[86:87], v[0:1] op_sel_hi:[1,0] neg_lo:[0,1] neg_hi:[0,1]
	v_pk_add_f32 v[102:103], v[102:103], v[0:1] op_sel_hi:[1,0] neg_lo:[0,1] neg_hi:[0,1]
	v_pk_add_f32 v[56:57], v[56:57], v[0:1] op_sel_hi:[1,0] neg_lo:[0,1] neg_hi:[0,1]
	v_pk_add_f32 v[72:73], v[72:73], v[0:1] op_sel_hi:[1,0] neg_lo:[0,1] neg_hi:[0,1]
	v_pk_add_f32 v[88:89], v[88:89], v[0:1] op_sel_hi:[1,0] neg_lo:[0,1] neg_hi:[0,1]
	v_pk_add_f32 v[104:105], v[104:105], v[0:1] op_sel_hi:[1,0] neg_lo:[0,1] neg_hi:[0,1]
	v_pk_add_f32 v[58:59], v[58:59], v[0:1] op_sel_hi:[1,0] neg_lo:[0,1] neg_hi:[0,1]
	v_pk_add_f32 v[74:75], v[74:75], v[0:1] op_sel_hi:[1,0] neg_lo:[0,1] neg_hi:[0,1]
	v_pk_add_f32 v[90:91], v[90:91], v[0:1] op_sel_hi:[1,0] neg_lo:[0,1] neg_hi:[0,1]
	v_pk_add_f32 v[106:107], v[106:107], v[0:1] op_sel_hi:[1,0] neg_lo:[0,1] neg_hi:[0,1]
	v_pk_add_f32 v[60:61], v[60:61], v[0:1] op_sel_hi:[1,0] neg_lo:[0,1] neg_hi:[0,1]
	v_pk_add_f32 v[76:77], v[76:77], v[0:1] op_sel_hi:[1,0] neg_lo:[0,1] neg_hi:[0,1]
	v_pk_add_f32 v[92:93], v[92:93], v[0:1] op_sel_hi:[1,0] neg_lo:[0,1] neg_hi:[0,1]
	v_pk_add_f32 v[108:109], v[108:109], v[0:1] op_sel_hi:[1,0] neg_lo:[0,1] neg_hi:[0,1]
	v_pk_add_f32 v[62:63], v[62:63], v[0:1] op_sel_hi:[1,0] neg_lo:[0,1] neg_hi:[0,1]
	v_pk_add_f32 v[78:79], v[78:79], v[0:1] op_sel_hi:[1,0] neg_lo:[0,1] neg_hi:[0,1]
	v_pk_add_f32 v[94:95], v[94:95], v[0:1] op_sel_hi:[1,0] neg_lo:[0,1] neg_hi:[0,1]
	v_pk_add_f32 v[110:111], v[110:111], v[0:1] op_sel_hi:[1,0] neg_lo:[0,1] neg_hi:[0,1]
	v_pk_add_f32 v[64:65], v[64:65], v[0:1] op_sel_hi:[1,0] neg_lo:[0,1] neg_hi:[0,1]
	v_pk_add_f32 v[80:81], v[80:81], v[0:1] op_sel_hi:[1,0] neg_lo:[0,1] neg_hi:[0,1]
	v_pk_add_f32 v[96:97], v[96:97], v[0:1] op_sel_hi:[1,0] neg_lo:[0,1] neg_hi:[0,1]
	v_pk_add_f32 v[112:113], v[112:113], v[0:1] op_sel_hi:[1,0] neg_lo:[0,1] neg_hi:[0,1]
	v_sub_f32_e32 v49, v49, v0
	v_sub_f32_e32 v48, v48, v0
	v_sub_f32_e32 v47, v47, v0
	v_sub_f32_e32 v46, v46, v0
	v_sub_f32_e32 v45, v45, v0
	v_sub_f32_e32 v44, v44, v0
	v_sub_f32_e32 v43, v43, v0
	v_sub_f32_e32 v42, v42, v0
	v_sub_f32_e32 v41, v41, v0
	v_sub_f32_e32 v40, v40, v0
	v_sub_f32_e32 v39, v39, v0
	v_sub_f32_e32 v38, v38, v0
	v_sub_f32_e32 v37, v37, v0
	v_sub_f32_e32 v36, v36, v0
	v_sub_f32_e32 v35, v35, v0
	v_sub_f32_e32 v34, v34, v0

; #define GLOAD(kt_, KR, VR) do { _Pragma("unroll") for (int i = 0; i < KCH; ++i) if (krow_[i] < 64) KR[i] = *(const u32x4*)(kbase + (size_t)((kt_) * 64 + krow_[i]) * HK * DQ + kcol_[i]); \
;     VR = *(const u32x4*)(vbase + (size_t)(kt_) * 4096 + vrow * 64 + vcol); } while (0)
; #define LSTORE(buf_, KR, VR) do { _Pragma("unroll") for (int i = 0; i < KCH; ++i) if (krow_[i] < 64) *(u32x4*)(sK + (buf_) * 64 * KROW + krow_[i] * KROW + kcol_[i]) = KR[i]; \
;     u16* d_ = sV + (buf_) * 64 * VROW + vrow * VROW + (vcol >> 4) * 16 + ((vcol >> 3) & 1) * 4; u32x2 lo_ = {VR.x, VR.y}, hi_ = {VR.z, VR.w}; *(u32x2*)d_ = lo_; *(u32x2*)(d_ + 8) = hi_; } while (0)
; template <int DQ>
; DI void attn_dense_item(const u16* __restrict__ Q, int qh, const u16* __restrict__ Kp, int HK, int kh, const u16* __restrict__ Vt,
;                         int S, int s0, int qblk, u16* __restrict__ MER, int ocol, float* __restrict__ ssqo, int slot, unsigned char* smem) {
;     ...
;   const u16* kbase = Kp + ((size_t)s0 * HK + kh) * DQ;
;   const u16* vbase = Vt + (size_t)s0 * HK * 64 + (size_t)(kh * 64) * S;
;   int krow_[KCH], kcol_[KCH];
; #pragma unroll
;   for (int i = 0; i < KCH; ++i) { const int c = tid + 512 * i; krow_[i] = c / CPR; kcol_[i] = (c - krow_[i] * CPR) * 8; }
;   const int vrow = tid >> 3, vcol = (tid & 7) * 8;
;   u32x4 krA[KCH], vrA, krB[KCH], vrB;
;     ...
;   const int nkt = S >> 6;
;   GLOAD(0, krA, vrA); GLOAD(1, krB, vrB); LSTORE(0, krA, vrA); LSTORE(1, krB, vrB);
;   GLOAD(2, krA, vrA); GLOAD(3, krB, vrB);
;   __syncthreads();
;   f32x16 o[2];
;   float lrun = 0.f;
;   f32x16 negm;
; #pragma unroll
;   for (int i = 0; i < 16; ++i) { o[0][i] = 0.f; o[1][i] = 0.f; negm[i] = 0.f; }
.LBB0_345:
	s_or_b64 exec, exec, s[4:5]
	v_sub_f32_e32 v34, 0, v0
	v_add_f32_e32 v0, 0, v62
	v_add_f32_e32 v0, v63, v0
	v_add_f32_e32 v0, v64, v0
	v_add_f32_e32 v0, v65, v0
	v_add_f32_e32 v0, v84, v0
	v_add_f32_e32 v0, v85, v0
	v_add_f32_e32 v0, v86, v0
	v_add_f32_e32 v0, v87, v0
	v_add_f32_e32 v0, v88, v0
	v_add_f32_e32 v0, v89, v0
	v_add_f32_e32 v0, v90, v0
	v_add_f32_e32 v0, v91, v0
	v_add_f32_e32 v0, v92, v0
	v_add_f32_e32 v0, v93, v0
	v_add_f32_e32 v0, v94, v0
	v_add_f32_e32 v0, v95, v0
	v_add_f32_e32 v0, v96, v0
	v_add_f32_e32 v0, v97, v0
	v_add_f32_e32 v0, v98, v0
	v_add_f32_e32 v0, v99, v0
	v_add_f32_e32 v0, v100, v0
	v_add_f32_e32 v0, v101, v0
	v_add_f32_e32 v0, v102, v0
	v_add_f32_e32 v0, v103, v0
	v_add_f32_e32 v0, v104, v0
	v_add_f32_e32 v0, v105, v0
	v_add_f32_e32 v0, v106, v0
	v_add_f32_e32 v0, v107, v0
	v_add_f32_e32 v0, v108, v0
	v_add_f32_e32 v0, v109, v0
	v_add_f32_e32 v0, v110, v0
	v_add_f32_e32 v0, v111, v0
	v_add_f32_e32 v0, v112, v0
	v_add_f32_e32 v0, v113, v0
	v_add_f32_e32 v0, v142, v0
	s_mov_b32 s4, 0xa000
	v_add_f32_e32 v0, v143, v0
	v_add_co_u32_e32 v50, vcc, s4, v80
	v_add_f32_e32 v0, v144, v0
	s_nop 0
	v_addc_co_u32_e32 v51, vcc, 0, v81, vcc
	v_add_f32_e32 v0, v145, v0
	global_load_dwordx4 v[142:145], v[50:51], off
	v_add_f32_e32 v0, v146, v0
	v_add_f32_e32 v0, v147, v0
	v_add_f32_e32 v0, v148, v0
	v_add_f32_e32 v0, v149, v0
	v_add_f32_e32 v0, v154, v0
	v_add_f32_e32 v0, v155, v0
	v_add_f32_e32 v0, v156, v0
	v_add_f32_e32 v0, v157, v0
	v_add_f32_e32 v0, v165, v0
	v_add_f32_e32 v0, v166, v0
	v_add_f32_e32 v0, v167, v0
	v_add_f32_e32 v0, v168, v0
	v_add_f32_e32 v0, v169, v0
	v_add_f32_e32 v0, v170, v0
	v_add_f32_e32 v0, v171, v0
	v_add_f32_e32 v0, v172, v0
	v_add_f32_e32 v0, v173, v0
	v_add_f32_e32 v0, v174, v0
	v_add_f32_e32 v0, v175, v0
	v_add_f32_e32 v0, v176, v0
	v_add_f32_e32 v0, v177, v0
	v_add_f32_e32 v0, v178, v0
	v_add_f32_e32 v0, v179, v0
	v_add_f32_e32 v0, v191, v0
	v_add_f32_e32 v0, v192, v0
	v_lshlrev_b64 v[50:51], 8, v[74:75]
	v_add_f32_e32 v165, v193, v0
	v_lshl_add_u64 v[50:51], v[50:51], 0, s[12:13]
	v_and_b32_e32 v0, 7, v82
	v_lshl_add_u64 v[50:51], v[76:77], 1, v[50:51]
	v_lshlrev_b32_e32 v0, 4, v0
	s_waitcnt lgkmcnt(0)
	s_barrier
	v_lshl_add_u64 v[154:155], s[90:91], 0, v[50:51]
	v_lshl_add_u64 v[50:51], s[14:15], 1, v[0:1]
	v_lshl_add_u64 v[50:51], v[78:79], 1, v[50:51]
	v_ashrrev_i32_e32 v151, 31, v150
	v_mov_b32_e32 v35, v34
	v_mov_b32_e32 v36, v34
	v_mov_b32_e32 v37, v34
	v_mov_b32_e32 v38, v34
	v_mov_b32_e32 v39, v34
	v_mov_b32_e32 v40, v34
	v_mov_b32_e32 v41, v34
	v_mov_b32_e32 v42, v34
	v_mov_b32_e32 v43, v34
	v_mov_b32_e32 v44, v34
	v_mov_b32_e32 v45, v34
	v_mov_b32_e32 v46, v34
	v_mov_b32_e32 v47, v34
	v_mov_b32_e32 v48, v34
	v_mov_b32_e32 v49, v34
	v_lshl_add_u64 v[156:157], s[90:91], 0, v[50:51]
	s_mov_b64 vcc, 0x252f8000
	v_lshl_add_u64 v[154:155], v[154:155], 0, s[10:11]
	v_lshl_add_u64 v[156:157], v[156:157], 0, s[10:11]
	v_lshl_add_u64 v[154:155], v[154:155], 0, vcc
	s_mov_b64 vcc, 0x26aec000
	v_lshl_add_u64 v[156:157], v[156:157], 0, vcc
	v_mov_b32_e32 v62, 0
	v_mov_b32_e32 v63, 0
	v_mov_b32_e32 v64, 0
	v_mov_b32_e32 v65, 0
	v_mov_b32_e32 v74, 0
	v_mov_b32_e32 v75, 0
	v_mov_b32_e32 v76, 0
	v_mov_b32_e32 v77, 0
	v_mov_b32_e32 v78, 0
	v_mov_b32_e32 v79, 0
	v_mov_b32_e32 v80, 0
	v_mov_b32_e32 v81, 0
	v_mov_b32_e32 v106, 0
	v_mov_b32_e32 v107, 0
	v_mov_b32_e32 v108, 0
	v_mov_b32_e32 v109, 0
	v_mov_b32_e32 v110, 0
	v_mov_b32_e32 v111, 0
	v_mov_b32_e32 v112, 0
	v_mov_b32_e32 v113, 0
	v_mov_b32_e32 v82, 0
	v_mov_b32_e32 v83, 0
	v_mov_b32_e32 v84, 0
	v_mov_b32_e32 v85, 0
	v_mov_b32_e32 v86, 0
	v_mov_b32_e32 v87, 0
	v_mov_b32_e32 v88, 0
	v_mov_b32_e32 v89, 0
	v_mov_b32_e32 v90, 0
	v_mov_b32_e32 v91, 0
	v_mov_b32_e32 v92, 0
	v_mov_b32_e32 v93, 0
	v_mov_b32_e32 v94, 0
	v_mov_b32_e32 v95, 0
	v_mov_b32_e32 v96, 0
	v_mov_b32_e32 v97, 0
	v_mov_b32_e32 v166, 0
	v_mov_b32_e32 v167, 0
	v_mov_b32_e32 v168, 0
	v_mov_b32_e32 v169, 0
	v_mov_b32_e32 v170, 0
	v_mov_b32_e32 v171, 0
	v_mov_b32_e32 v172, 0
	v_mov_b32_e32 v173, 0
	v_mov_b32_e32 v174, 0
	v_mov_b32_e32 v175, 0
	v_mov_b32_e32 v176, 0
	v_mov_b32_e32 v177, 0
	v_mov_b32_e32 v178, 0
	v_mov_b32_e32 v179, 0
	v_mov_b32_e32 v191, 0
	v_mov_b32_e32 v192, 0
	v_mov_b32_e32 v193, 0
	v_mov_b32_e32 v194, 0
	v_mov_b32_e32 v195, 0
	v_mov_b32_e32 v196, 0
	v_mov_b32_e32 v197, 0
	v_mov_b32_e32 v198, 0
	v_mov_b32_e32 v199, 0
	v_mov_b32_e32 v200, 0
	v_mov_b32_e32 v201, 0
	v_mov_b32_e32 v202, 0
	v_mov_b32_e32 v203, 0
	v_mov_b32_e32 v204, 0
	s_mov_b32 s12, 6
	s_branch .LBB0_348

.Lgqa_B_356:
	s_cmp_ge_u32 s12, s23
	s_cbranch_scc1 .Lgqa_B_ls_end
	s_mov_b64 vcc, 0x4000
	v_lshl_add_u64 v[50:51], v[154:155], 0, vcc
	s_mov_b64 vcc, 0x2000
	v_lshl_add_u64 v[52:53], v[156:157], 0, vcc
	s_and_saveexec_b64 s[4:5], s[0:1]
	s_cbranch_execz .Lgqa_B_359
	global_load_dwordx4 v[130:133], v[154:155], off
.Lgqa_B_359:
	s_or_b64 exec, exec, s[4:5]
	global_load_dwordx4 v[138:141], v[156:157], off
	s_and_saveexec_b64 s[4:5], s[0:1]
	s_cbranch_execz .Lgqa_B_346
	global_load_dwordx4 v[134:137], v[50:51], off
.Lgqa_B_346:
	s_or_b64 exec, exec, s[4:5]
	global_load_dwordx4 v[142:145], v[52:53], off
.Lgqa_B_ls_end:
	v_add_f32_e32 v165, v62, v165
	v_add_f32_e32 v242, v63, v64
	v_add_f32_e32 v165, v65, v165
	v_add_f32_e32 v242, v74, v242
	v_add_f32_e32 v165, v75, v165
	v_add_f32_e32 v242, v76, v242
	v_add_f32_e32 v165, v77, v165
	v_add_f32_e32 v242, v78, v242
	v_add_f32_e32 v165, v79, v165
	v_add_f32_e32 v242, v80, v242
	v_add_f32_e32 v165, v81, v165
	v_add_f32_e32 v242, v106, v242
	s_waitcnt lgkmcnt(6)
	v_mfma_f32_32x32x16_bf16 v[50:65], v[214:217], v[114:117], v[34:49]
	ds_read_b128 v[214:217], v0 offset:4704
	v_add_f32_e32 v165, v107, v165
	v_add_f32_e32 v242, v108, v242
	v_add_f32_e32 v165, v109, v165
	v_add_f32_e32 v242, v110, v242
	v_add_f32_e32 v165, v111, v165
	s_waitcnt lgkmcnt(6)
	v_mfma_f32_32x32x16_bf16 v[50:65], v[218:221], v[118:121], v[50:65]
	ds_read_b128 v[218:221], v0
	v_add_f32_e32 v242, v112, v242
	v_add_f32_e32 v165, v113, v165
	v_add_f32_e32 v242, v82, v242
	v_add_f32_e32 v165, v83, v165
	v_add_f32_e32 v242, v84, v242
	s_waitcnt lgkmcnt(6)
	v_mfma_f32_32x32x16_bf16 v[50:65], v[222:225], v[122:125], v[50:65]
	ds_read_b128 v[222:225], v0 offset:32
	v_add_f32_e32 v165, v85, v165
	v_add_f32_e32 v242, v86, v242
	v_add_f32_e32 v165, v87, v165
	v_add_f32_e32 v242, v88, v242
	v_add_f32_e32 v165, v89, v165
	s_waitcnt lgkmcnt(6)
	v_mfma_f32_32x32x16_bf16 v[50:65], v[226:229], v[126:129], v[50:65]
	ds_read_b128 v[226:229], v0 offset:64
	v_add_f32_e32 v242, v90, v242
	v_add_f32_e32 v165, v91, v165
	v_add_f32_e32 v242, v92, v242
	v_add_f32_e32 v165, v93, v165
	v_add_f32_e32 v242, v94, v242
	s_waitcnt lgkmcnt(6)
	v_mfma_f32_32x32x16_bf16 v[66:81], v[230:233], v[114:117], v[34:49]
	ds_read_b128 v[230:233], v0 offset:96
	v_add_f32_e32 v165, v95, v165
	v_add_f32_e32 v242, v96, v242
	v_add_f32_e32 v165, v97, v165
	v_add_f32_e32 v242, v166, v242
	s_waitcnt lgkmcnt(6)
	v_mfma_f32_32x32x16_bf16 v[66:81], v[234:237], v[118:121], v[66:81]
	ds_read_b128 v[234:237], v0 offset:13824
	v_add_f32_e32 v165, v167, v165
	v_add_f32_e32 v242, v168, v242
	v_add_f32_e32 v165, v169, v165
	v_add_f32_e32 v242, v170, v242
	s_waitcnt lgkmcnt(6)
	v_mfma_f32_32x32x16_bf16 v[66:81], v[238:241], v[122:125], v[66:81]
	ds_read_b128 v[238:241], v0 offset:13856
	v_add_f32_e32 v165, v171, v165
	v_add_f32_e32 v242, v172, v242
	v_add_f32_e32 v165, v173, v165
	v_add_f32_e32 v242, v174, v242
	v_max3_f32 v146, v50, v51, v52
	v_max3_f32 v146, v146, v53, v54
	s_waitcnt lgkmcnt(6)
	v_mfma_f32_32x32x16_bf16 v[66:81], v[214:217], v[126:129], v[66:81]
	ds_read_b128 v[214:217], v0 offset:13888
	v_add_f32_e32 v165, v175, v165
	v_add_f32_e32 v242, v176, v242
	v_add_f32_e32 v165, v177, v165
	v_add_f32_e32 v242, v178, v242
	v_max3_f32 v146, v146, v55, v56
	v_max3_f32 v146, v146, v57, v58
	s_waitcnt lgkmcnt(6)
	v_mfma_f32_32x32x16_bf16 v[98:113], v[218:221], v[114:117], v[34:49]
	ds_read_b128 v[218:221], v0 offset:13920
	v_add_f32_e32 v165, v179, v165
	v_add_f32_e32 v242, v191, v242
	v_add_f32_e32 v165, v192, v165
	v_add_f32_e32 v242, v193, v242
	v_max3_f32 v146, v146, v59, v60
	v_max3_f32 v146, v146, v61, v62
	s_waitcnt lgkmcnt(6)
	v_mfma_f32_32x32x16_bf16 v[98:113], v[222:225], v[118:121], v[98:113]
	ds_read_b128 v[206:209], v0 offset:36864
	v_add_f32_e32 v165, v194, v165
	v_add_f32_e32 v242, v195, v242
	v_add_f32_e32 v165, v196, v165
	v_add_f32_e32 v242, v197, v242
	v_max3_f32 v146, v146, v63, v64
	v_max3_f32 v146, v146, v65, v65
	s_waitcnt lgkmcnt(6)
	v_mfma_f32_32x32x16_bf16 v[98:113], v[226:229], v[122:125], v[98:113]
	ds_read_b128 v[210:213], v0 offset:41472
	v_add_f32_e32 v165, v198, v165
	v_add_f32_e32 v242, v199, v242
	v_add_f32_e32 v165, v200, v165
	v_add_f32_e32 v242, v201, v242
	v_max3_f32 v146, v146, v66, v67
	v_max3_f32 v146, v146, v68, v69
	s_waitcnt lgkmcnt(6)
	v_mfma_f32_32x32x16_bf16 v[98:113], v[230:233], v[126:129], v[98:113]
	ds_read_b128 v[222:225], v0 offset:36896
	v_add_f32_e32 v165, v202, v165
	v_add_f32_e32 v242, v203, v242
	v_add_f32_e32 v165, v204, v165
	v_add_f32_e32 v165, v242, v165
	v_max3_f32 v146, v146, v70, v71
	v_max3_f32 v146, v146, v72, v73
	s_waitcnt lgkmcnt(6)
	v_mfma_f32_32x32x16_bf16 v[82:97], v[234:237], v[114:117], v[34:49]
	ds_read_b128 v[226:229], v0 offset:41504
	v_max3_f32 v146, v146, v74, v75
	v_max3_f32 v146, v146, v76, v77
	s_waitcnt lgkmcnt(6)
	v_mfma_f32_32x32x16_bf16 v[82:97], v[238:241], v[118:121], v[82:97]
	ds_read_b128 v[230:233], v0 offset:36928
	v_max3_f32 v146, v146, v78, v79
	v_max3_f32 v146, v146, v80, v81
	s_waitcnt lgkmcnt(6)
	v_mfma_f32_32x32x16_bf16 v[82:97], v[214:217], v[122:125], v[82:97]
	ds_read_b128 v[234:237], v0 offset:41536
	s_waitcnt lgkmcnt(6)
	v_mfma_f32_32x32x16_bf16 v[82:97], v[218:221], v[126:129], v[82:97]
	v_max3_f32 v146, v146, v98, v99
	v_max3_f32 v146, v146, v100, v101
	v_max3_f32 v146, v146, v102, v103
	v_max3_f32 v146, v146, v104, v105
	v_max3_f32 v146, v146, v106, v107
	v_max3_f32 v146, v146, v108, v109
	v_max3_f32 v146, v146, v110, v111
	v_max3_f32 v146, v146, v112, v113
	s_nop 3
	v_max3_f32 v146, v146, v82, v83
	v_max3_f32 v146, v146, v84, v85
	v_max3_f32 v146, v146, v86, v87
	v_max3_f32 v146, v146, v88, v89
	v_max3_f32 v146, v146, v90, v91
	v_max3_f32 v146, v146, v92, v93
	v_max3_f32 v146, v146, v94, v95
	v_max3_f32 v146, v146, v96, v97
	v_mov_b32_e32 v147, v146
	s_nop 1
	v_permlane32_swap_b32_e32 v146, v147
	v_max_f32_e32 v146, v146, v147
	v_cmp_lt_f32_e32 vcc, s50, v146
	s_cbranch_vccz .LBB0_350
	v_max_f32_e32 v146, v146, v146
	v_max_f32_e32 v146, 0, v146
	v_exp_f32_e64 v148, -v146
	v_pk_add_f32 v[98:99], v[98:99], v[146:147] op_sel_hi:[1,0] neg_lo:[0,1] neg_hi:[0,1]
	v_pk_add_f32 v[66:67], v[66:67], v[146:147] op_sel_hi:[1,0] neg_lo:[0,1] neg_hi:[0,1]
	v_pk_add_f32 v[50:51], v[50:51], v[146:147] op_sel_hi:[1,0] neg_lo:[0,1] neg_hi:[0,1]
	v_mul_f32_e32 v165, v165, v148
	v_pk_mul_f32 v[16:17], v[16:17], v[148:149] op_sel_hi:[1,0]
	v_pk_mul_f32 v[14:15], v[14:15], v[148:149] op_sel_hi:[1,0]
	v_pk_mul_f32 v[12:13], v[12:13], v[148:149] op_sel_hi:[1,0]
	v_pk_mul_f32 v[10:11], v[10:11], v[148:149] op_sel_hi:[1,0]
	v_pk_mul_f32 v[8:9], v[8:9], v[148:149] op_sel_hi:[1,0]
	v_pk_mul_f32 v[6:7], v[6:7], v[148:149] op_sel_hi:[1,0]
	v_pk_mul_f32 v[4:5], v[4:5], v[148:149] op_sel_hi:[1,0]
	v_pk_mul_f32 v[2:3], v[2:3], v[148:149] op_sel_hi:[1,0]
	v_pk_mul_f32 v[32:33], v[32:33], v[148:149] op_sel_hi:[1,0]
	v_pk_mul_f32 v[30:31], v[30:31], v[148:149] op_sel_hi:[1,0]
	v_pk_mul_f32 v[28:29], v[28:29], v[148:149] op_sel_hi:[1,0]
	v_pk_mul_f32 v[26:27], v[26:27], v[148:149] op_sel_hi:[1,0]
	v_pk_mul_f32 v[24:25], v[24:25], v[148:149] op_sel_hi:[1,0]
	v_pk_mul_f32 v[22:23], v[22:23], v[148:149] op_sel_hi:[1,0]
	v_pk_mul_f32 v[20:21], v[20:21], v[148:149] op_sel_hi:[1,0]
	v_pk_mul_f32 v[18:19], v[18:19], v[148:149] op_sel_hi:[1,0]
	v_pk_add_f32 v[82:83], v[82:83], v[146:147] op_sel_hi:[1,0] neg_lo:[0,1] neg_hi:[0,1]
	v_pk_add_f32 v[100:101], v[100:101], v[146:147] op_sel_hi:[1,0] neg_lo:[0,1] neg_hi:[0,1]
	v_pk_add_f32 v[68:69], v[68:69], v[146:147] op_sel_hi:[1,0] neg_lo:[0,1] neg_hi:[0,1]
	v_pk_add_f32 v[52:53], v[52:53], v[146:147] op_sel_hi:[1,0] neg_lo:[0,1] neg_hi:[0,1]
	v_pk_add_f32 v[84:85], v[84:85], v[146:147] op_sel_hi:[1,0] neg_lo:[0,1] neg_hi:[0,1]
	v_pk_add_f32 v[102:103], v[102:103], v[146:147] op_sel_hi:[1,0] neg_lo:[0,1] neg_hi:[0,1]
	v_pk_add_f32 v[70:71], v[70:71], v[146:147] op_sel_hi:[1,0] neg_lo:[0,1] neg_hi:[0,1]
	v_pk_add_f32 v[54:55], v[54:55], v[146:147] op_sel_hi:[1,0] neg_lo:[0,1] neg_hi:[0,1]
	v_pk_add_f32 v[86:87], v[86:87], v[146:147] op_sel_hi:[1,0] neg_lo:[0,1] neg_hi:[0,1]
	v_pk_add_f32 v[104:105], v[104:105], v[146:147] op_sel_hi:[1,0] neg_lo:[0,1] neg_hi:[0,1]
	v_pk_add_f32 v[72:73], v[72:73], v[146:147] op_sel_hi:[1,0] neg_lo:[0,1] neg_hi:[0,1]
	v_pk_add_f32 v[56:57], v[56:57], v[146:147] op_sel_hi:[1,0] neg_lo:[0,1] neg_hi:[0,1]
	v_pk_add_f32 v[88:89], v[88:89], v[146:147] op_sel_hi:[1,0] neg_lo:[0,1] neg_hi:[0,1]
	v_pk_add_f32 v[106:107], v[106:107], v[146:147] op_sel_hi:[1,0] neg_lo:[0,1] neg_hi:[0,1]
	v_pk_add_f32 v[74:75], v[74:75], v[146:147] op_sel_hi:[1,0] neg_lo:[0,1] neg_hi:[0,1]
	v_pk_add_f32 v[58:59], v[58:59], v[146:147] op_sel_hi:[1,0] neg_lo:[0,1] neg_hi:[0,1]
	v_pk_add_f32 v[90:91], v[90:91], v[146:147] op_sel_hi:[1,0] neg_lo:[0,1] neg_hi:[0,1]
	v_pk_add_f32 v[108:109], v[108:109], v[146:147] op_sel_hi:[1,0] neg_lo:[0,1] neg_hi:[0,1]
	v_pk_add_f32 v[76:77], v[76:77], v[146:147] op_sel_hi:[1,0] neg_lo:[0,1] neg_hi:[0,1]
	v_pk_add_f32 v[60:61], v[60:61], v[146:147] op_sel_hi:[1,0] neg_lo:[0,1] neg_hi:[0,1]
	v_pk_add_f32 v[92:93], v[92:93], v[146:147] op_sel_hi:[1,0] neg_lo:[0,1] neg_hi:[0,1]
	v_pk_add_f32 v[110:111], v[110:111], v[146:147] op_sel_hi:[1,0] neg_lo:[0,1] neg_hi:[0,1]
	v_pk_add_f32 v[78:79], v[78:79], v[146:147] op_sel_hi:[1,0] neg_lo:[0,1] neg_hi:[0,1]
	v_pk_add_f32 v[62:63], v[62:63], v[146:147] op_sel_hi:[1,0] neg_lo:[0,1] neg_hi:[0,1]
	v_pk_add_f32 v[94:95], v[94:95], v[146:147] op_sel_hi:[1,0] neg_lo:[0,1] neg_hi:[0,1]
	v_pk_add_f32 v[112:113], v[112:113], v[146:147] op_sel_hi:[1,0] neg_lo:[0,1] neg_hi:[0,1]
	v_pk_add_f32 v[80:81], v[80:81], v[146:147] op_sel_hi:[1,0] neg_lo:[0,1] neg_hi:[0,1]
	v_pk_add_f32 v[64:65], v[64:65], v[146:147] op_sel_hi:[1,0] neg_lo:[0,1] neg_hi:[0,1]
	v_pk_add_f32 v[96:97], v[96:97], v[146:147] op_sel_hi:[1,0] neg_lo:[0,1] neg_hi:[0,1]
	v_sub_f32_e32 v49, v49, v146
	v_sub_f32_e32 v48, v48, v146
	v_sub_f32_e32 v47, v47, v146
	v_sub_f32_e32 v46, v46, v146
	v_sub_f32_e32 v45, v45, v146
	v_sub_f32_e32 v44, v44, v146
	v_sub_f32_e32 v43, v43, v146
	v_sub_f32_e32 v42, v42, v146
	v_sub_f32_e32 v41, v41, v146
	v_sub_f32_e32 v40, v40, v146
	v_sub_f32_e32 v39, v39, v146
	v_sub_f32_e32 v38, v38, v146
	v_sub_f32_e32 v37, v37, v146
	v_sub_f32_e32 v36, v36, v146
	v_sub_f32_e32 v35, v35, v146
	v_sub_f32_e32 v34, v34, v146
